# residual-stream stores of the two residual GEMM epilogues written through (sc0 sc1)
# baseline (speedup 1.0000x reference)
;     __device__ __forceinline__ void operator()(const f32x4 (&acc)[2][2][4][2], const Unit& u, int wr, int wc, int fr, int fq) const {
;     ...
;         const bool isctx = u.pm >= 128;
;         const float* inb = isctx ? in_ctx : in_lat; float* outb = isctx ? out_ctx : out_lat;
;         const int pml = isctx ? u.pm - 128 : u.pm;
;         const float* gp = gate + (size_t)(isctx ? 16 : (u.pm >> 3)) * 6144;
;         const int row0 = pml * BM + wr * 64 + fr, col0 = u.pn * BM + wc * 32 + 4 * fq;
;         f32x4 gv[2][2];
; #pragma unroll
;         for (int bj = 0; bj < 2; ++bj)
; #pragma unroll
;             for (int n = 0; n < 2; ++n) gv[bj][n] = *(const f32x4*)(gp + col0 + bj * HALF + n * 16);
; #pragma unroll
;         for (int ai = 0; ai < 2; ++ai)
; #pragma unroll
;             for (int m = 0; m < 4; ++m) { const size_t ro = (size_t)(row0 + ai * HALF + m * 16) * 1024 + col0;
; #pragma unroll
;                 for (int bj = 0; bj < 2; ++bj)
; #pragma unroll
;                     for (int n = 0; n < 2; ++n) { const f32x4 x = *(const f32x4*)(inb + ro + bj * HALF + n * 16);
;                         *(f32x4*)(outb + ro + bj * HALF + n * 16) = x + gv[bj][n] * acc[ai][bj][m][n]; } }
.LBB0_979:
	s_and_b64 s[2:3], exec, s[26:27]
	v_readlane_b32 s2, v255, 39
	v_readlane_b32 s16, v255, 41
	v_readlane_b32 s3, v255, 40
	v_readlane_b32 s17, v255, 42
	s_cselect_b32 s3, s3, s17
	s_cselect_b32 s2, s2, s16
	s_cselect_b32 s17, s65, s43
	s_cselect_b32 s16, s64, s42
	s_lshl_b64 s[18:19], s[28:29], 2
	s_add_u32 s18, s52, s18
	s_addc_u32 s19, s53, s19
	s_lshl_b32 s5, s20, 8
	s_add_i32 s21, s5, 0xffff8000
	s_and_b64 s[26:27], exec, s[26:27]
	s_cselect_b32 s5, s21, s5
	v_add_u32_e32 v174, s5, v160
	v_lshl_or_b32 v172, s11, 8, v161
	v_ashrrev_i32_e32 v175, 31, v174
	v_ashrrev_i32_e32 v173, 31, v172
	v_lshlrev_b64 v[146:147], 10, v[174:175]
	v_lshl_add_u64 v[146:147], v[146:147], 0, v[172:173]
	v_lshlrev_b64 v[170:171], 2, v[146:147]
	v_lshl_add_u64 v[130:131], v[172:173], 2, s[18:19]
	v_lshl_add_u64 v[150:151], s[2:3], 0, v[170:171]
	global_load_dwordx4 v[142:145], v[130:131], off
	global_load_dwordx4 v[138:141], v[130:131], off offset:64
	global_load_dwordx4 v[134:137], v[130:131], off offset:512
	s_nop 0
	global_load_dwordx4 v[130:133], v[130:131], off offset:576
	v_lshl_add_u64 v[152:153], s[16:17], 0, v[170:171]
	s_mov_b64 s[98:99], 0x10000
	v_lshl_add_u64 v[176:177], v[150:151], 0, s[98:99]
	v_lshl_add_u64 v[178:179], v[152:153], 0, s[98:99]
	s_mov_b64 s[98:99], 0x20000
	v_lshl_add_u64 v[180:181], v[150:151], 0, s[98:99]
	v_lshl_add_u64 v[182:183], v[152:153], 0, s[98:99]
	s_mov_b64 s[98:99], 0x30000
	v_lshl_add_u64 v[184:185], v[150:151], 0, s[98:99]
	v_lshl_add_u64 v[186:187], v[152:153], 0, s[98:99]
	s_mov_b64 s[98:99], 0x80000
	v_lshl_add_u64 v[188:189], v[150:151], 0, s[98:99]
	v_lshl_add_u64 v[190:191], v[152:153], 0, s[98:99]
	s_mov_b64 s[98:99], 0x90000
	v_lshl_add_u64 v[192:193], v[150:151], 0, s[98:99]
	v_lshl_add_u64 v[194:195], v[152:153], 0, s[98:99]
	s_mov_b64 s[98:99], 0xa0000
	v_lshl_add_u64 v[196:197], v[150:151], 0, s[98:99]
	v_lshl_add_u64 v[198:199], v[152:153], 0, s[98:99]
	s_mov_b64 s[98:99], 0xb0000
	v_lshl_add_u64 v[200:201], v[150:151], 0, s[98:99]
	v_lshl_add_u64 v[202:203], v[152:153], 0, s[98:99]
	global_load_dwordx4 v[204:207], v[150:151], off
	global_load_dwordx4 v[212:215], v[150:151], off offset:64
	global_load_dwordx4 v[224:227], v[150:151], off offset:512
	global_load_dwordx4 v[228:231], v[150:151], off offset:576
	global_load_dwordx4 v[232:235], v[176:177], off
	global_load_dwordx4 v[236:239], v[176:177], off offset:64
	global_load_dwordx4 v[240:243], v[176:177], off offset:512
	global_load_dwordx4 v[244:247], v[176:177], off offset:576
	global_load_dwordx4 v[248:251], v[180:181], off
	global_load_dwordx4 v[218:221], v[180:181], off offset:64
	global_load_dwordx4 v[172:175], v[180:181], off offset:512
	s_waitcnt vmcnt(10)
	v_pk_fma_f32 v[206:207], v[128:129], v[144:145], v[206:207]
	v_pk_fma_f32 v[204:205], v[126:127], v[142:143], v[204:205]
	global_store_dwordx4 v[152:153], v[204:207], off sc0 sc1
	global_load_dwordx4 v[126:129], v[180:181], off offset:576
	s_waitcnt vmcnt(11)
	v_pk_fma_f32 v[214:215], v[124:125], v[140:141], v[214:215]
	v_pk_fma_f32 v[212:213], v[122:123], v[138:139], v[212:213]
	global_store_dwordx4 v[152:153], v[212:215], off offset:64 sc0 sc1
	global_load_dwordx4 v[204:207], v[184:185], off
	global_load_dwordx4 v[122:125], v[184:185], off offset:64
	s_waitcnt vmcnt(13)
	v_pk_fma_f32 v[226:227], v[112:113], v[136:137], v[226:227]
	v_pk_fma_f32 v[224:225], v[110:111], v[134:135], v[224:225]
	global_store_dwordx4 v[152:153], v[224:227], off offset:512 sc0 sc1
	global_load_dwordx4 v[212:215], v[184:185], off offset:512
	global_load_dwordx4 v[110:113], v[184:185], off offset:576
	s_waitcnt vmcnt(15)
	v_pk_fma_f32 v[230:231], v[104:105], v[132:133], v[230:231]
	v_pk_fma_f32 v[228:229], v[102:103], v[130:131], v[228:229]
	global_store_dwordx4 v[152:153], v[228:231], off offset:576 sc0 sc1
	global_load_dwordx4 v[224:227], v[188:189], off
	global_load_dwordx4 v[102:105], v[188:189], off offset:64
	s_waitcnt vmcnt(17)
	v_pk_fma_f32 v[234:235], v[120:121], v[144:145], v[234:235]
	v_pk_fma_f32 v[232:233], v[118:119], v[142:143], v[232:233]
	global_store_dwordx4 v[178:179], v[232:235], off sc0 sc1
	global_load_dwordx4 v[228:231], v[188:189], off offset:512
	global_load_dwordx4 v[118:121], v[188:189], off offset:576
	s_waitcnt vmcnt(19)
	v_pk_fma_f32 v[238:239], v[116:117], v[140:141], v[238:239]
	v_pk_fma_f32 v[236:237], v[114:115], v[138:139], v[236:237]
	global_store_dwordx4 v[178:179], v[236:239], off offset:64 sc0 sc1
	global_load_dwordx4 v[232:235], v[192:193], off
	global_load_dwordx4 v[114:117], v[192:193], off offset:64
	s_waitcnt vmcnt(21)
	v_pk_fma_f32 v[242:243], v[96:97], v[136:137], v[242:243]
	v_pk_fma_f32 v[240:241], v[94:95], v[134:135], v[240:241]
	global_store_dwordx4 v[178:179], v[240:243], off offset:512 sc0 sc1
	global_load_dwordx4 v[236:239], v[192:193], off offset:512
	global_load_dwordx4 v[94:97], v[192:193], off offset:576
	s_waitcnt vmcnt(23)
	v_pk_fma_f32 v[246:247], v[88:89], v[132:133], v[246:247]
	v_pk_fma_f32 v[244:245], v[86:87], v[130:131], v[244:245]
	global_store_dwordx4 v[178:179], v[244:247], off offset:576 sc0 sc1
	global_load_dwordx4 v[240:243], v[196:197], off
	global_load_dwordx4 v[86:89], v[196:197], off offset:64
	s_waitcnt vmcnt(25)
;     __device__ __forceinline__ void operator()(const f32x4 (&acc)[2][2][4][2], const Unit& u, int wr, int wc, int fr, int fq) const {
;     ...
;             for (int m = 0; m < 4; ++m) { const size_t ro = (size_t)(row0 + ai * HALF + m * 16) * 1024 + col0;
; #pragma unroll
;                 for (int bj = 0; bj < 2; ++bj)
; #pragma unroll
;                     for (int n = 0; n < 2; ++n) { const f32x4 x = *(const f32x4*)(inb + ro + bj * HALF + n * 16);
;                         *(f32x4*)(outb + ro + bj * HALF + n * 16) = x + gv[bj][n] * acc[ai][bj][m][n]; } }
	v_pk_fma_f32 v[250:251], v[108:109], v[144:145], v[250:251]
	v_pk_fma_f32 v[248:249], v[106:107], v[142:143], v[248:249]
	global_store_dwordx4 v[182:183], v[248:251], off sc0 sc1
	global_load_dwordx4 v[244:247], v[196:197], off offset:512
	global_load_dwordx4 v[106:109], v[196:197], off offset:576
	s_waitcnt vmcnt(27)
	v_pk_fma_f32 v[220:221], v[100:101], v[140:141], v[220:221]
	v_pk_fma_f32 v[218:219], v[98:99], v[138:139], v[218:219]
	global_store_dwordx4 v[182:183], v[218:221], off offset:64 sc0 sc1
	global_load_dwordx4 v[248:251], v[200:201], off
	global_load_dwordx4 v[98:101], v[200:201], off offset:64
	s_waitcnt vmcnt(29)
	v_pk_fma_f32 v[174:175], v[80:81], v[136:137], v[174:175]
	v_pk_fma_f32 v[172:173], v[78:79], v[134:135], v[172:173]
	global_store_dwordx4 v[182:183], v[172:175], off offset:512 sc0 sc1
	global_load_dwordx4 v[218:221], v[200:201], off offset:512
	global_load_dwordx4 v[78:81], v[200:201], off offset:576
	s_waitcnt vmcnt(30)
	v_pk_fma_f32 v[128:129], v[76:77], v[132:133], v[128:129]
	v_pk_fma_f32 v[126:127], v[74:75], v[130:131], v[126:127]
	global_store_dwordx4 v[182:183], v[126:129], off offset:576 sc0 sc1
	s_waitcnt vmcnt(29)
	v_pk_fma_f32 v[206:207], v[92:93], v[144:145], v[206:207]
	v_pk_fma_f32 v[204:205], v[90:91], v[142:143], v[204:205]
	global_store_dwordx4 v[186:187], v[204:207], off sc0 sc1
	s_waitcnt vmcnt(29)
	v_pk_fma_f32 v[124:125], v[84:85], v[140:141], v[124:125]
	v_pk_fma_f32 v[122:123], v[82:83], v[138:139], v[122:123]
	global_store_dwordx4 v[186:187], v[122:125], off offset:64 sc0 sc1
	s_waitcnt vmcnt(28)
	v_pk_fma_f32 v[214:215], v[72:73], v[136:137], v[214:215]
	v_pk_fma_f32 v[212:213], v[70:71], v[134:135], v[212:213]
	global_store_dwordx4 v[186:187], v[212:215], off offset:512 sc0 sc1
	s_waitcnt vmcnt(28)
	v_pk_fma_f32 v[112:113], v[68:69], v[132:133], v[112:113]
	v_pk_fma_f32 v[110:111], v[66:67], v[130:131], v[110:111]
	global_store_dwordx4 v[186:187], v[110:113], off offset:576 sc0 sc1
	s_waitcnt vmcnt(27)
	v_pk_fma_f32 v[226:227], v[64:65], v[144:145], v[226:227]
	v_pk_fma_f32 v[224:225], v[62:63], v[142:143], v[224:225]
	global_store_dwordx4 v[190:191], v[224:227], off sc0 sc1
	s_waitcnt vmcnt(27)
	v_pk_fma_f32 v[104:105], v[60:61], v[140:141], v[104:105]
	v_pk_fma_f32 v[102:103], v[58:59], v[138:139], v[102:103]
	global_store_dwordx4 v[190:191], v[102:105], off offset:64 sc0 sc1
	s_waitcnt vmcnt(26)
	v_pk_fma_f32 v[230:231], v[48:49], v[136:137], v[230:231]
	v_pk_fma_f32 v[228:229], v[46:47], v[134:135], v[228:229]
	global_store_dwordx4 v[190:191], v[228:231], off offset:512 sc0 sc1
	s_waitcnt vmcnt(26)
	v_pk_fma_f32 v[120:121], v[44:45], v[132:133], v[120:121]
	v_pk_fma_f32 v[118:119], v[42:43], v[130:131], v[118:119]
	global_store_dwordx4 v[190:191], v[118:121], off offset:576 sc0 sc1
	s_waitcnt vmcnt(25)
	v_pk_fma_f32 v[234:235], v[56:57], v[144:145], v[234:235]
	v_pk_fma_f32 v[232:233], v[54:55], v[142:143], v[232:233]
	global_store_dwordx4 v[194:195], v[232:235], off sc0 sc1
	s_waitcnt vmcnt(25)
	v_pk_fma_f32 v[116:117], v[52:53], v[140:141], v[116:117]
	v_pk_fma_f32 v[114:115], v[50:51], v[138:139], v[114:115]
	global_store_dwordx4 v[194:195], v[114:117], off offset:64 sc0 sc1
	s_waitcnt vmcnt(24)
	v_pk_fma_f32 v[238:239], v[32:33], v[136:137], v[238:239]
	v_pk_fma_f32 v[236:237], v[30:31], v[134:135], v[236:237]
	global_store_dwordx4 v[194:195], v[236:239], off offset:512 sc0 sc1
	s_waitcnt vmcnt(24)
	v_pk_fma_f32 v[96:97], v[28:29], v[132:133], v[96:97]
	v_pk_fma_f32 v[94:95], v[26:27], v[130:131], v[94:95]
	global_store_dwordx4 v[194:195], v[94:97], off offset:576 sc0 sc1
	s_waitcnt vmcnt(23)
	v_pk_fma_f32 v[242:243], v[40:41], v[144:145], v[242:243]
	v_pk_fma_f32 v[240:241], v[38:39], v[142:143], v[240:241]
	global_store_dwordx4 v[198:199], v[240:243], off sc0 sc1
	s_waitcnt vmcnt(23)
	v_pk_fma_f32 v[88:89], v[36:37], v[140:141], v[88:89]
	v_pk_fma_f32 v[86:87], v[34:35], v[138:139], v[86:87]
	global_store_dwordx4 v[198:199], v[86:89], off offset:64 sc0 sc1
	s_waitcnt vmcnt(22)
	v_pk_fma_f32 v[246:247], v[16:17], v[136:137], v[246:247]
	v_pk_fma_f32 v[244:245], v[14:15], v[134:135], v[244:245]
	global_store_dwordx4 v[198:199], v[244:247], off offset:512 sc0 sc1
	s_waitcnt vmcnt(22)
	v_pk_fma_f32 v[108:109], v[12:13], v[132:133], v[108:109]
	v_pk_fma_f32 v[106:107], v[10:11], v[130:131], v[106:107]
	global_store_dwordx4 v[198:199], v[106:109], off offset:576 sc0 sc1
	s_waitcnt vmcnt(21)
	v_pk_fma_f32 v[250:251], v[24:25], v[144:145], v[250:251]
	v_pk_fma_f32 v[248:249], v[22:23], v[142:143], v[248:249]
	global_store_dwordx4 v[202:203], v[248:251], off sc0 sc1
	s_waitcnt vmcnt(21)
	v_pk_fma_f32 v[100:101], v[20:21], v[140:141], v[100:101]
	v_pk_fma_f32 v[98:99], v[18:19], v[138:139], v[98:99]
	global_store_dwordx4 v[202:203], v[98:101], off offset:64 sc0 sc1
	s_waitcnt vmcnt(20)
	v_pk_fma_f32 v[220:221], v[8:9], v[136:137], v[220:221]
	v_pk_fma_f32 v[218:219], v[6:7], v[134:135], v[218:219]
	global_store_dwordx4 v[202:203], v[218:221], off offset:512 sc0 sc1
	s_waitcnt vmcnt(20)
	v_pk_fma_f32 v[80:81], v[4:5], v[132:133], v[80:81]
	v_pk_fma_f32 v[78:79], v[2:3], v[130:131], v[78:79]
	global_store_dwordx4 v[202:203], v[78:81], off offset:576 sc0 sc1
	s_mov_b64 s[2:3], 0

;     __device__ __forceinline__ void operator()(const f32x4 (&acc)[2][2][4][2], const Unit& u, int wr, int wc, int fr, int fq) const {
;     ...
;         const bool isctx = u.pm >= 128;
;         const float* inb = isctx ? in_ctx : in_lat; float* outb = isctx ? out_ctx : out_lat;
;         const int pml = isctx ? u.pm - 128 : u.pm;
;         const float* gp = gate + (size_t)(isctx ? 16 : (u.pm >> 3)) * 6144;
;         const int row0 = pml * BM + wr * 64 + fr, col0 = u.pn * BM + wc * 32 + 4 * fq;
;         f32x4 gv[2][2];
; #pragma unroll
;         for (int bj = 0; bj < 2; ++bj)
; #pragma unroll
;             for (int n = 0; n < 2; ++n) gv[bj][n] = *(const f32x4*)(gp + col0 + bj * HALF + n * 16);
; #pragma unroll
;         for (int ai = 0; ai < 2; ++ai)
; #pragma unroll
;             for (int m = 0; m < 4; ++m) { const size_t ro = (size_t)(row0 + ai * HALF + m * 16) * 1024 + col0;
; #pragma unroll
;                 for (int bj = 0; bj < 2; ++bj)
; #pragma unroll
;                     for (int n = 0; n < 2; ++n) { const f32x4 x = *(const f32x4*)(inb + ro + bj * HALF + n * 16);
;                         *(f32x4*)(outb + ro + bj * HALF + n * 16) = x + gv[bj][n] * acc[ai][bj][m][n]; } }
.LBB0_1199:
	s_and_b64 s[2:3], exec, s[16:17]
	s_cselect_b32 s3, s65, s43
	s_cselect_b32 s2, s64, s42
	s_lshl_b64 s[26:27], s[26:27], 2
	s_add_u32 s26, s50, s26
	s_addc_u32 s27, s51, s27
	s_lshl_b32 s5, s18, 8
	s_add_i32 s19, s5, 0xffff8000
	s_and_b64 s[16:17], exec, s[16:17]
	s_cselect_b32 s5, s19, s5
	v_add_u32_e32 v174, s5, v160
	v_lshl_or_b32 v130, s11, 8, v161
	v_ashrrev_i32_e32 v175, 31, v174
	v_ashrrev_i32_e32 v131, 31, v130
	v_lshlrev_b64 v[146:147], 12, v[174:175]
	v_lshlrev_b64 v[172:173], 2, v[130:131]
	v_lshl_add_u64 v[146:147], s[2:3], 0, v[146:147]
	v_lshl_add_u64 v[130:131], s[26:27], 0, v[172:173]
	v_lshl_add_u64 v[170:171], v[146:147], 0, v[172:173]
	global_load_dwordx4 v[142:145], v[130:131], off
	global_load_dwordx4 v[138:141], v[130:131], off offset:64
	global_load_dwordx4 v[134:137], v[130:131], off offset:512
	s_nop 0
	global_load_dwordx4 v[130:133], v[130:131], off offset:576
	s_nop 0
	s_mov_b64 s[98:99], 0x10000
	v_lshl_add_u64 v[176:177], v[170:171], 0, s[98:99]
	s_mov_b64 s[98:99], 0x20000
	v_lshl_add_u64 v[178:179], v[170:171], 0, s[98:99]
	s_mov_b64 s[98:99], 0x30000
	v_lshl_add_u64 v[180:181], v[170:171], 0, s[98:99]
	s_mov_b64 s[98:99], 0x80000
	v_lshl_add_u64 v[182:183], v[170:171], 0, s[98:99]
	s_mov_b64 s[98:99], 0x90000
	v_lshl_add_u64 v[184:185], v[170:171], 0, s[98:99]
	s_mov_b64 s[98:99], 0xa0000
	v_lshl_add_u64 v[186:187], v[170:171], 0, s[98:99]
	s_mov_b64 s[98:99], 0xb0000
	v_lshl_add_u64 v[188:189], v[170:171], 0, s[98:99]
	global_load_dwordx4 v[204:207], v[170:171], off
	global_load_dwordx4 v[212:215], v[170:171], off offset:64
	global_load_dwordx4 v[224:227], v[170:171], off offset:512
	global_load_dwordx4 v[228:231], v[170:171], off offset:576
	global_load_dwordx4 v[232:235], v[176:177], off
	global_load_dwordx4 v[236:239], v[176:177], off offset:64
	global_load_dwordx4 v[240:243], v[176:177], off offset:512
	global_load_dwordx4 v[244:247], v[176:177], off offset:576
	global_load_dwordx4 v[248:251], v[178:179], off
	global_load_dwordx4 v[218:221], v[178:179], off offset:64
	global_load_dwordx4 v[172:175], v[178:179], off offset:512
	global_load_dwordx4 v[150:153], v[178:179], off offset:576
	global_load_dwordx4 v[190:193], v[180:181], off
	global_load_dwordx4 v[194:197], v[180:181], off offset:64
	global_load_dwordx4 v[198:201], v[180:181], off offset:512
	s_waitcnt vmcnt(14)
	v_pk_fma_f32 v[206:207], v[128:129], v[144:145], v[206:207]
	v_pk_fma_f32 v[204:205], v[126:127], v[142:143], v[204:205]
	global_store_dwordx4 v[170:171], v[204:207], off sc0 sc1
	global_load_dwordx4 v[126:129], v[180:181], off offset:576
	s_waitcnt vmcnt(15)
	v_pk_fma_f32 v[214:215], v[124:125], v[140:141], v[214:215]
	v_pk_fma_f32 v[212:213], v[122:123], v[138:139], v[212:213]
	global_store_dwordx4 v[170:171], v[212:215], off offset:64 sc0 sc1
	global_load_dwordx4 v[204:207], v[182:183], off
	global_load_dwordx4 v[122:125], v[182:183], off offset:64
	s_waitcnt vmcnt(17)
	v_pk_fma_f32 v[226:227], v[112:113], v[136:137], v[226:227]
	v_pk_fma_f32 v[224:225], v[110:111], v[134:135], v[224:225]
	global_store_dwordx4 v[170:171], v[224:227], off offset:512 sc0 sc1
	global_load_dwordx4 v[212:215], v[182:183], off offset:512
	global_load_dwordx4 v[110:113], v[182:183], off offset:576
	s_waitcnt vmcnt(19)
	v_pk_fma_f32 v[230:231], v[104:105], v[132:133], v[230:231]
	v_pk_fma_f32 v[228:229], v[102:103], v[130:131], v[228:229]
	global_store_dwordx4 v[170:171], v[228:231], off offset:576 sc0 sc1
	global_load_dwordx4 v[224:227], v[184:185], off
	global_load_dwordx4 v[102:105], v[184:185], off offset:64
	s_waitcnt vmcnt(21)
	v_pk_fma_f32 v[234:235], v[120:121], v[144:145], v[234:235]
	v_pk_fma_f32 v[232:233], v[118:119], v[142:143], v[232:233]
	global_store_dwordx4 v[176:177], v[232:235], off sc0 sc1
	global_load_dwordx4 v[228:231], v[184:185], off offset:512
	global_load_dwordx4 v[118:121], v[184:185], off offset:576
	s_waitcnt vmcnt(23)
	v_pk_fma_f32 v[238:239], v[116:117], v[140:141], v[238:239]
	v_pk_fma_f32 v[236:237], v[114:115], v[138:139], v[236:237]
	global_store_dwordx4 v[176:177], v[236:239], off offset:64 sc0 sc1
	global_load_dwordx4 v[232:235], v[186:187], off
	global_load_dwordx4 v[114:117], v[186:187], off offset:64
	s_waitcnt vmcnt(25)
	v_pk_fma_f32 v[242:243], v[96:97], v[136:137], v[242:243]
	v_pk_fma_f32 v[240:241], v[94:95], v[134:135], v[240:241]
	global_store_dwordx4 v[176:177], v[240:243], off offset:512 sc0 sc1
	global_load_dwordx4 v[236:239], v[186:187], off offset:512
	global_load_dwordx4 v[94:97], v[186:187], off offset:576
	s_waitcnt vmcnt(27)
	v_pk_fma_f32 v[246:247], v[88:89], v[132:133], v[246:247]
	v_pk_fma_f32 v[244:245], v[86:87], v[130:131], v[244:245]
	global_store_dwordx4 v[176:177], v[244:247], off offset:576 sc0 sc1
	global_load_dwordx4 v[240:243], v[188:189], off
	global_load_dwordx4 v[86:89], v[188:189], off offset:64
	s_waitcnt vmcnt(29)
;     __device__ __forceinline__ void operator()(const f32x4 (&acc)[2][2][4][2], const Unit& u, int wr, int wc, int fr, int fq) const {
;     ...
;             for (int m = 0; m < 4; ++m) { const size_t ro = (size_t)(row0 + ai * HALF + m * 16) * 1024 + col0;
; #pragma unroll
;                 for (int bj = 0; bj < 2; ++bj)
; #pragma unroll
;                     for (int n = 0; n < 2; ++n) { const f32x4 x = *(const f32x4*)(inb + ro + bj * HALF + n * 16);
;                         *(f32x4*)(outb + ro + bj * HALF + n * 16) = x + gv[bj][n] * acc[ai][bj][m][n]; } }
	v_pk_fma_f32 v[250:251], v[108:109], v[144:145], v[250:251]
	v_pk_fma_f32 v[248:249], v[106:107], v[142:143], v[248:249]
	global_store_dwordx4 v[178:179], v[248:251], off sc0 sc1
	global_load_dwordx4 v[244:247], v[188:189], off offset:512
	global_load_dwordx4 v[106:109], v[188:189], off offset:576
	s_waitcnt vmcnt(31)
	v_pk_fma_f32 v[220:221], v[100:101], v[140:141], v[220:221]
	v_pk_fma_f32 v[218:219], v[98:99], v[138:139], v[218:219]
	global_store_dwordx4 v[178:179], v[218:221], off offset:64 sc0 sc1
	s_waitcnt vmcnt(31)
	v_pk_fma_f32 v[174:175], v[80:81], v[136:137], v[174:175]
	v_pk_fma_f32 v[172:173], v[78:79], v[134:135], v[172:173]
	global_store_dwordx4 v[178:179], v[172:175], off offset:512 sc0 sc1
	s_waitcnt vmcnt(31)
	v_pk_fma_f32 v[152:153], v[76:77], v[132:133], v[152:153]
	v_pk_fma_f32 v[150:151], v[74:75], v[130:131], v[150:151]
	global_store_dwordx4 v[178:179], v[150:153], off offset:576 sc0 sc1
	s_waitcnt vmcnt(31)
	v_pk_fma_f32 v[192:193], v[92:93], v[144:145], v[192:193]
	v_pk_fma_f32 v[190:191], v[90:91], v[142:143], v[190:191]
	global_store_dwordx4 v[180:181], v[190:193], off sc0 sc1
	s_waitcnt vmcnt(31)
	v_pk_fma_f32 v[196:197], v[84:85], v[140:141], v[196:197]
	v_pk_fma_f32 v[194:195], v[82:83], v[138:139], v[194:195]
	global_store_dwordx4 v[180:181], v[194:197], off offset:64 sc0 sc1
	s_waitcnt vmcnt(31)
	v_pk_fma_f32 v[200:201], v[72:73], v[136:137], v[200:201]
	v_pk_fma_f32 v[198:199], v[70:71], v[134:135], v[198:199]
	global_store_dwordx4 v[180:181], v[198:201], off offset:512 sc0 sc1
	s_waitcnt vmcnt(30)
	v_pk_fma_f32 v[128:129], v[68:69], v[132:133], v[128:129]
	v_pk_fma_f32 v[126:127], v[66:67], v[130:131], v[126:127]
	global_store_dwordx4 v[180:181], v[126:129], off offset:576 sc0 sc1
	s_waitcnt vmcnt(29)
	v_pk_fma_f32 v[206:207], v[64:65], v[144:145], v[206:207]
	v_pk_fma_f32 v[204:205], v[62:63], v[142:143], v[204:205]
	global_store_dwordx4 v[182:183], v[204:207], off sc0 sc1
	s_waitcnt vmcnt(29)
	v_pk_fma_f32 v[124:125], v[60:61], v[140:141], v[124:125]
	v_pk_fma_f32 v[122:123], v[58:59], v[138:139], v[122:123]
	global_store_dwordx4 v[182:183], v[122:125], off offset:64 sc0 sc1
	s_waitcnt vmcnt(28)
	v_pk_fma_f32 v[214:215], v[48:49], v[136:137], v[214:215]
	v_pk_fma_f32 v[212:213], v[46:47], v[134:135], v[212:213]
	global_store_dwordx4 v[182:183], v[212:215], off offset:512 sc0 sc1
	s_waitcnt vmcnt(28)
	v_pk_fma_f32 v[112:113], v[44:45], v[132:133], v[112:113]
	v_pk_fma_f32 v[110:111], v[42:43], v[130:131], v[110:111]
	global_store_dwordx4 v[182:183], v[110:113], off offset:576 sc0 sc1
	s_waitcnt vmcnt(27)
	v_pk_fma_f32 v[226:227], v[56:57], v[144:145], v[226:227]
	v_pk_fma_f32 v[224:225], v[54:55], v[142:143], v[224:225]
	global_store_dwordx4 v[184:185], v[224:227], off sc0 sc1
	s_waitcnt vmcnt(27)
	v_pk_fma_f32 v[104:105], v[52:53], v[140:141], v[104:105]
	v_pk_fma_f32 v[102:103], v[50:51], v[138:139], v[102:103]
	global_store_dwordx4 v[184:185], v[102:105], off offset:64 sc0 sc1
	s_waitcnt vmcnt(26)
	v_pk_fma_f32 v[230:231], v[32:33], v[136:137], v[230:231]
	v_pk_fma_f32 v[228:229], v[30:31], v[134:135], v[228:229]
	global_store_dwordx4 v[184:185], v[228:231], off offset:512 sc0 sc1
	s_waitcnt vmcnt(26)
	v_pk_fma_f32 v[120:121], v[28:29], v[132:133], v[120:121]
	v_pk_fma_f32 v[118:119], v[26:27], v[130:131], v[118:119]
	global_store_dwordx4 v[184:185], v[118:121], off offset:576 sc0 sc1
	s_waitcnt vmcnt(25)
	v_pk_fma_f32 v[234:235], v[40:41], v[144:145], v[234:235]
	v_pk_fma_f32 v[232:233], v[38:39], v[142:143], v[232:233]
	global_store_dwordx4 v[186:187], v[232:235], off sc0 sc1
	s_waitcnt vmcnt(25)
	v_pk_fma_f32 v[116:117], v[36:37], v[140:141], v[116:117]
	v_pk_fma_f32 v[114:115], v[34:35], v[138:139], v[114:115]
	global_store_dwordx4 v[186:187], v[114:117], off offset:64 sc0 sc1
	s_waitcnt vmcnt(24)
	v_pk_fma_f32 v[238:239], v[16:17], v[136:137], v[238:239]
	v_pk_fma_f32 v[236:237], v[14:15], v[134:135], v[236:237]
	global_store_dwordx4 v[186:187], v[236:239], off offset:512 sc0 sc1
	s_waitcnt vmcnt(24)
	v_pk_fma_f32 v[96:97], v[12:13], v[132:133], v[96:97]
	v_pk_fma_f32 v[94:95], v[10:11], v[130:131], v[94:95]
	global_store_dwordx4 v[186:187], v[94:97], off offset:576 sc0 sc1
	s_waitcnt vmcnt(23)
	v_pk_fma_f32 v[242:243], v[24:25], v[144:145], v[242:243]
	v_pk_fma_f32 v[240:241], v[22:23], v[142:143], v[240:241]
	global_store_dwordx4 v[188:189], v[240:243], off sc0 sc1
	s_waitcnt vmcnt(23)
	v_pk_fma_f32 v[88:89], v[20:21], v[140:141], v[88:89]
	v_pk_fma_f32 v[86:87], v[18:19], v[138:139], v[86:87]
	global_store_dwordx4 v[188:189], v[86:89], off offset:64 sc0 sc1
	s_waitcnt vmcnt(22)
	v_pk_fma_f32 v[246:247], v[8:9], v[136:137], v[246:247]
	v_pk_fma_f32 v[244:245], v[6:7], v[134:135], v[244:245]
	global_store_dwordx4 v[188:189], v[244:247], off offset:512 sc0 sc1
	s_waitcnt vmcnt(22)
	v_pk_fma_f32 v[108:109], v[4:5], v[132:133], v[108:109]
	v_pk_fma_f32 v[106:107], v[2:3], v[130:131], v[106:107]
	global_store_dwordx4 v[188:189], v[106:109], off offset:576 sc0 sc1
	s_mov_b64 s[2:3], 0
